# adds P0 rebalance: the 96 mod-vector workgroups take fewer weight-conversion items
# speedup vs baseline: 1.0215x; 1.0082x over previous
; __device__ __forceinline__ void p0_phase(const Args& a, LAS unsigned char* lds, int bid, int G) {
;     ...
;     constexpr int I0 = 16 * 80, I1 = 8 * 12, I2 = 4 * 8, I2b = 4 * 8, I3 = 8 * 16, I4 = 8 * 16, I5 = 16 * 16, I6 = 16 * 88, I7 = 44 * 16;
;     constexpr int NIT = I0 + I1 + I2 + I2b + I3 + I4 + I5 + I6 + I7;
;     for (int it = bid; it < NIT; it += G) {
;         int r = it;
;         if (r < I0) { wt_item(a.in[6], 1024, 4896, (bf16_t*)(ws + WS_WIN), 1, r, 80, tile); continue; } r -= I0;
.LBB0_28:
	s_cmpk_gt_i32 s2, 0xfdf
	s_cbranch_scc1 .LBB0_121
	s_add_u32 s6, s30, 0x1f00000
	s_addc_u32 s7, s31, 0
	s_add_u32 s10, s30, 0x1400000
	s_addc_u32 s11, s31, 0
	s_add_u32 s12, s30, 0x1200000
	s_addc_u32 s13, s31, 0
	s_add_u32 s14, s30, 0x1000000
	s_addc_u32 s15, s31, 0
	s_add_u32 s16, s30, 0xf80000
	s_addc_u32 s17, s31, 0
	s_add_u32 s18, s30, 0xf00000
	s_addc_u32 s19, s31, 0
	s_add_u32 s20, s30, 0xe00000
	s_addc_u32 s21, s31, 0
	s_add_u32 s22, s30, 0x400000
	v_mul_u32_u24_e32 v0, 0x84, v18
	v_lshlrev_b32_e32 v1, 1, v152
	s_addc_u32 s23, s31, 0
	v_add3_u32 v6, 0, v0, v1
	v_lshlrev_b32_e32 v0, 3, v254
	s_waitcnt lgkmcnt(0)
	s_cmp_lg_u64 s[70:71], 0
	v_lshrrev_b32_e32 v14, 3, v254
	v_and_b32_e32 v0, 56, v0
	s_cselect_b64 s[24:25], -1, 0
	s_cmp_lg_u64 s[66:67], 0
	v_mul_u32_u24_e32 v1, 0x84, v14
	v_lshlrev_b32_e32 v2, 1, v0
	s_cselect_b64 s[26:27], -1, 0
	s_lshl_b32 s3, s2, 2
	s_mov_b32 s9, 0
	v_add_u32_e32 v7, 8, v152
	v_or_b32_e32 v8, 16, v152
	v_add_u32_e32 v9, 24, v152
	v_or_b32_e32 v10, 32, v152
	v_add_u32_e32 v11, 40, v152
	v_or_b32_e32 v12, 48, v152
	v_add_u32_e32 v13, 56, v152
	v_add3_u32 v15, 0, v1, v2
	v_mov_b32_e32 v1, 0
	v_lshlrev_b32_e32 v16, 9, v14
	s_lshl_b32 s58, s2, 6
	s_lshl_b32 s59, s86, 6
	s_add_i32 s60, s3, 0x3cb80
	s_lshl_b32 s61, s86, 2
	s_lshl_b32 s78, s2, 3
	s_lshl_b32 s79, s86, 3
	s_movk_i32 s88, 0x320
	s_movk_i32 s89, 0x4c80
	v_lshlrev_b32_e32 v2, 1, v0
	v_lshlrev_b32_e32 v17, 2, v18
	v_mov_b32_e32 v19, 0x400
	v_cndmask_b32_e64 v20, 0, 1, s[24:25]
	s_mov_b32 s90, s2
	s_cmpk_lt_u32 s2, 0x60
	s_cbranch_scc1 .Lp0_stage2_init
	s_sub_i32 s90, s2, 0x60
	s_movk_i32 s98, 0xa0
	s_movk_i32 s99, 0xd20
	s_branch .Lp0_derive
.Lp0_stage2_init:
	s_add_i32 s90, s2, 0xd20
	s_movk_i32 s98, 0x100
	s_movk_i32 s99, 0xfe0
.Lp0_derive:
	s_lshl_b32 s58, s90, 6
	s_lshl_b32 s59, s98, 6
	s_lshl_b32 s60, s90, 2
	s_add_i32 s60, s60, 0x3cb80
	s_lshl_b32 s61, s98, 2
	s_lshl_b32 s78, s90, 3
	s_lshl_b32 s79, s98, 3
	s_branch .LBB0_32

; __device__ __forceinline__ void p0_phase(const Args& a, LAS unsigned char* lds, int bid, int G) {
;     ...
;     for (int it = bid; it < NIT; it += G) {
;         int r = it;
.LBB0_31:
	s_add_i32 s90, s90, s98
	s_add_i32 s58, s58, s59
	s_add_i32 s60, s60, s61
	s_add_i32 s78, s78, s79
	s_cmp_lt_i32 s90, s99
	s_cbranch_scc1 .LBB0_32
	s_cmpk_eq_i32 s99, 0xfe0
	s_cbranch_scc1 .LBB0_121
	s_branch .Lp0_stage2_init

; __global__ void __launch_bounds__(NTHR) mk_fwd(Args a) {
	.amdhsa_kernel _Z6mk_fwd4Args
		.amdhsa_group_segment_fixed_size 0
		.amdhsa_private_segment_fixed_size 0
		.amdhsa_kernarg_size 528
		.amdhsa_user_sgpr_count 2
		.amdhsa_user_sgpr_dispatch_ptr 0
		.amdhsa_user_sgpr_queue_ptr 0
		.amdhsa_user_sgpr_kernarg_segment_ptr 1
		.amdhsa_user_sgpr_dispatch_id 0
		.amdhsa_user_sgpr_kernarg_preload_length 0
		.amdhsa_user_sgpr_kernarg_preload_offset 0
		.amdhsa_user_sgpr_private_segment_size 0
		.amdhsa_uses_dynamic_stack 0
		.amdhsa_enable_private_segment 0
		.amdhsa_system_sgpr_workgroup_id_x 1
		.amdhsa_system_sgpr_workgroup_id_y 0
		.amdhsa_system_sgpr_workgroup_id_z 0
		.amdhsa_system_sgpr_workgroup_info 0
		.amdhsa_system_vgpr_workitem_id 2
		.amdhsa_next_free_vgpr 256
		.amdhsa_next_free_sgpr 102
		.amdhsa_accum_offset 256
		.amdhsa_reserve_vcc 1
		.amdhsa_float_round_mode_32 0
		.amdhsa_float_round_mode_16_64 0
		.amdhsa_float_denorm_mode_32 3
		.amdhsa_float_denorm_mode_16_64 3
		.amdhsa_dx10_clamp 1
		.amdhsa_ieee_mode 1
		.amdhsa_fp16_overflow 0
		.amdhsa_tg_split 0
		.amdhsa_exception_fp_ieee_invalid_op 0
		.amdhsa_exception_fp_denorm_src 0
		.amdhsa_exception_fp_ieee_div_zero 0
		.amdhsa_exception_fp_ieee_overflow 0
		.amdhsa_exception_fp_ieee_underflow 0
		.amdhsa_exception_fp_ieee_inexact 0
		.amdhsa_exception_int_div_zero 0
	.end_amdhsa_kernel

; __global__ void __launch_bounds__(NTHR) mk_fwd(Args a) {
amdhsa.kernels:
  - .agpr_count:     0
    .args:
      - .offset:         0
        .size:           272
        .value_kind:     by_value
      - .offset:         272
        .size:           4
        .value_kind:     hidden_block_count_x
      - .offset:         276
        .size:           4
        .value_kind:     hidden_block_count_y
      - .offset:         280
        .size:           4
        .value_kind:     hidden_block_count_z
      - .offset:         284
        .size:           2
        .value_kind:     hidden_group_size_x
      - .offset:         286
        .size:           2
        .value_kind:     hidden_group_size_y
      - .offset:         288
        .size:           2
        .value_kind:     hidden_group_size_z
      - .offset:         290
        .size:           2
        .value_kind:     hidden_remainder_x
      - .offset:         292
        .size:           2
        .value_kind:     hidden_remainder_y
      - .offset:         294
        .size:           2
        .value_kind:     hidden_remainder_z
      - .offset:         312
        .size:           8
        .value_kind:     hidden_global_offset_x
      - .offset:         320
        .size:           8
        .value_kind:     hidden_global_offset_y
      - .offset:         328
        .size:           8
        .value_kind:     hidden_global_offset_z
      - .offset:         336
        .size:           2
        .value_kind:     hidden_grid_dims
      - .offset:         360
        .size:           8
        .value_kind:     hidden_multigrid_sync_arg
      - .offset:         392
        .size:           4
        .value_kind:     hidden_dynamic_lds_size
    .group_segment_fixed_size: 0
    .kernarg_segment_align: 8
    .kernarg_segment_size: 528
    .language:       OpenCL C
    .language_version:
      - 2
      - 0
    .max_flat_workgroup_size: 512
    .name:           _Z6mk_fwd4Args
    .private_segment_fixed_size: 0
    .sgpr_count:     108
    .sgpr_spill_count: 9
    .symbol:         _Z6mk_fwd4Args.kd
    .uniform_work_group_size: 1
    .uses_dynamic_stack: false
    .vgpr_count:     256
    .vgpr_spill_count: 0
    .wavefront_size: 64
